# P1 loop LDS-DMA loads in saddr form (no 64-bit VALU address adds); P3/P4 epilogue: first vmcnt wait moved after all operand loads
# speedup vs baseline: 1.0180x; 1.0180x over previous
;     __device__ __forceinline__ void operator()(f32x4 (&acc)[2][2][4][2], const Unit& u, int wr, int wc, int fr, int fq) const {
;         const int b = u.b; const size_t goff = (b == 0) ? S_G0 : (b == 1 ? S_G1 : S_G2);
;         const int row0 = u.pm * BM + wr * 64 + fr, col0 = u.pn * BM + wc * 32 + 8 * fq;
;         const bf16_t* gb = P + goff + (size_t)(u.pm * BM + wr * 64) * LDP + u.pn * BM;
;         const unsigned go = (unsigned)(fr * LDP + wc * 32 + 8 * fq);
;         u32x4 gw[2][4][2];
; #pragma unroll
;         for (int ai = 0; ai < 2; ++ai)
; #pragma unroll
;             for (int m = 0; m < 4; ++m)
; #pragma unroll
;                 for (int bj = 0; bj < 2; ++bj) gw[ai][m][bj] = *(const u32x4*)(gb + (ai * HALF + m * 16) * LDP + bj * HALF + go);
; #pragma unroll
;         for (int ai = 0; ai < 2; ++ai)
; #pragma unroll
;             for (int m = 0; m < 4; ++m)
; #pragma unroll
;                 for (int bj = 0; bj < 2; ++bj) {
;                     const u32x4 g = gw[ai][m][bj];
;                     f32x4 v0 = acc[ai][bj][m][0], v1 = acc[ai][bj][m][1];
;                     v0[0] *= bf_lo(g.x); v0[1] *= bf_hi(g.x); v0[2] *= bf_lo(g.y); v0[3] *= bf_hi(g.y); v1[0] *= bf_lo(g.z); v1[1] *= bf_hi(g.z); v1[2] *= bf_lo(g.w); v1[3] *= bf_hi(g.w);
.LBB0_34:
	s_cmp_eq_u32 s42, 1
	s_mov_b32 s0, 0xe000000
	s_cselect_b32 s0, s0, 0x10000000
	s_lshl_b32 s1, s51, 8
	s_add_i32 s16, s1, s49
	s_lshl_b32 s40, s43, 8
	s_cmp_lg_u32 s42, 0
	s_cselect_b32 s0, s0, 0xa000000
	s_lshl_b32 s0, s0, 1
	s_add_u32 s14, s70, s0
	s_addc_u32 s15, s71, 0
	s_ashr_i32 s17, s16, 31
	s_lshl_b64 s[0:1], s[16:17], 11
	s_add_u32 s14, s14, s0
	s_addc_u32 s15, s15, s1
	s_ashr_i32 s41, s40, 31
	s_lshl_b64 s[0:1], s[40:41], 1
	s_add_u32 s0, s14, s0
	s_addc_u32 s1, s15, s1
	v_lshl_add_u64 v[44:45], s[0:1], 0, v[212:213]
	v_add_co_u32_e32 v46, vcc, s11, v44
	global_load_dwordx4 v[40:43], v212, s[0:1]
	global_load_dwordx4 v[72:75], v212, s[0:1] offset:256
	v_addc_co_u32_e32 v47, vcc, 0, v45, vcc
	global_load_dwordx4 v[76:79], v[46:47], off
	global_load_dwordx4 v[112:115], v[46:47], off offset:256
	v_add_co_u32_e32 v46, vcc, s33, v44
	s_mov_b32 s0, 0x48000
	s_nop 0
	v_addc_co_u32_e32 v47, vcc, 0, v45, vcc
	global_load_dwordx4 v[116:119], v[46:47], off
	global_load_dwordx4 v[152:155], v[46:47], off offset:256
	v_add_co_u32_e32 v46, vcc, s10, v44
	s_cmp_lg_u32 s42, 2
	s_nop 0
	v_addc_co_u32_e32 v47, vcc, 0, v45, vcc
	global_load_dwordx4 v[156:159], v[46:47], off
	global_load_dwordx4 v[192:195], v[46:47], off offset:256
	v_add_co_u32_e32 v46, vcc, s69, v44
	s_nop 1
	v_addc_co_u32_e32 v47, vcc, 0, v45, vcc
	global_load_dwordx4 v[188:191], v[46:47], off
	global_load_dwordx4 v[176:179], v[46:47], off offset:256
	v_add_co_u32_e32 v46, vcc, s0, v44
	s_mov_b32 s0, 0x50000
	s_nop 0
	v_addc_co_u32_e32 v47, vcc, 0, v45, vcc
	global_load_dwordx4 v[172:175], v[46:47], off
	global_load_dwordx4 v[160:163], v[46:47], off offset:256
	v_add_co_u32_e32 v46, vcc, s0, v44
	s_mov_b32 s0, 0x58000
	s_nop 0
	v_addc_co_u32_e32 v47, vcc, 0, v45, vcc
	v_add_co_u32_e32 v44, vcc, s0, v44
	global_load_dwordx4 v[148:151], v[46:47], off
	global_load_dwordx4 v[128:131], v[46:47], off offset:256
	v_addc_co_u32_e32 v45, vcc, 0, v45, vcc
	global_load_dwordx4 v[108:111], v[44:45], off
	global_load_dwordx4 v[88:91], v[44:45], off offset:256
	s_waitcnt vmcnt(8)
	v_lshlrev_b32_e32 v208, 16, v42
	v_lshlrev_b32_e32 v44, 16, v40
	v_and_b32_e32 v45, 0xffff0000, v40
	v_lshlrev_b32_e32 v40, 16, v41
	v_and_b32_e32 v41, 0xffff0000, v41
	v_and_b32_e32 v209, 0xffff0000, v42
	v_lshlrev_b32_e32 v42, 16, v43
	v_and_b32_e32 v43, 0xffff0000, v43
	s_cselect_b64 s[0:1], -1, 0
	s_cmp_eq_u32 s42, 2
	v_pk_mul_f32 v[44:45], v[60:61], v[44:45]
	v_pk_mul_f32 v[46:47], v[62:63], v[40:41]
	v_pk_mul_f32 v[40:41], v[56:57], v[208:209]
	v_pk_mul_f32 v[42:43], v[58:59], v[42:43]
	s_mov_b64 s[42:43], -1
	s_cbranch_scc1 .LBB0_36
	s_mov_b64 s[42:43], 0

; #define PG8_STAGE(bufoff, gbase, voff) do { _Pragma("unroll") for (int _i = 0; _i < 2; ++_i) \
;         __builtin_amdgcn_global_load_lds((const unsigned*)((const char*)(gbase) + (voff)[_i]), (LAS unsigned*)(lds + (bufoff) + ldsw + _i * 8192), 16, 0, 0); } while (0)
; #define PG8_LDA(dst, b, h) do { _Pragma("unroll") for (int m = 0; m < 4; ++m) _Pragma("unroll") for (int k = 0; k < 2; ++k) dst[m][k] = *(const LAS bf16x8*)(lds + PG8_SA(b, h) + aoff + m * 2048 + k * 1024); } while (0)
; #define PG8_LDB(dst, b, h) do { _Pragma("unroll") for (int n = 0; n < 2; ++n) _Pragma("unroll") for (int k = 0; k < 2; ++k) dst[n][k] = *(const LAS bf16x8*)(lds + PG8_SB(b, h) + boff + n * 2048 + k * 1024); } while (0)
; #define PG8_MMA(ai, bj, At, Bt) do { __builtin_amdgcn_s_setprio(1); _Pragma("unroll") for (int m = 0; m < 4; ++m) _Pragma("unroll") for (int n = 0; n < 2; ++n) _Pragma("unroll") for (int k = 0; k < 2; ++k) \
;         acc[ai][bj][m][n] = __builtin_amdgcn_mfma_f32_16x16x32_bf16(Bt[n][k], At[m][k], acc[ai][bj][m][n], 0, 0, 0); __builtin_amdgcn_s_setprio(0); } while (0)
; #define PG8_WAIT_V(n) asm volatile("s_waitcnt vmcnt(" #n ")" ::: "memory")
; #define PG8_WAIT_L(n) asm volatile("s_waitcnt lgkmcnt(" #n ")" ::: "memory")
; #define PG8_BAR __builtin_amdgcn_s_barrier()
; #define PG8_SCHED __builtin_amdgcn_sched_barrier(0)
; template <class Epi, class Sched>
; __device__ __forceinline__ void gemm_phase(LAS unsigned char* lds, const Gemm g, const Sched& S, const Epi& E) {
;     ...
;             PG8_LDB(B0, 0, 0); PG8_LDB(B1, 0, 1); PG8_SCHED; PG8_LDA(At, 0, 0); PG8_STAGE(PG8_SA(1, 1), a1 + hstepA, voffA);
;             PG8_WAIT_V(8); PG8_WAIT_L(0); PG8_BAR; PG8_MMA(0, 0, At, B0); PG8_MMA(0, 1, At, B1); PG8_BAR; PG8_SCHED;
;             PG8_LDA(At, 0, 1); PG8_STAGE(PG8_SB(0, 0), b2, voffB); PG8_STAGE(PG8_SB(0, 1), b2 + hstepB, voffB); PG8_STAGE(PG8_SA(0, 0), a2, voffA);
;             PG8_WAIT_V(8); PG8_WAIT_L(0); PG8_BAR; PG8_MMA(1, 0, At, B0); PG8_MMA(1, 1, At, B1); PG8_BAR; PG8_SCHED;
.Lp1_nobar:
.LBB0_280:
	s_add_u32 s26, s24, 0xfffc0080
	s_addc_u32 s27, s25, -1
	s_add_i32 s44, 0, 0x10000
	s_cmp_eq_u32 s43, 12
	s_cselect_b32 s37, s6, s27
	s_cselect_b32 s36, s14, s26
	v_add_u32_e32 v145, s44, v165
	s_cselect_b32 s27, s15, s42
	s_cselect_b32 s26, s17, s19
	s_add_i32 s46, 0, 0x14000
	ds_read_b128 v[148:151], v145
	ds_read_b128 v[152:155], v145 offset:1024
	ds_read_b128 v[156:159], v145 offset:2048
	ds_read_b128 v[160:163], v145 offset:3072
	v_add_u32_e32 v145, s46, v165
	ds_read_b128 v[168:171], v145
	ds_read_b128 v[172:175], v145 offset:1024
	ds_read_b128 v[176:179], v145 offset:2048
	ds_read_b128 v[180:183], v145 offset:3072
	s_add_i32 m0, s52, 0xc000
	ds_read_b128 v[184:187], v167
	ds_read_b128 v[188:191], v167 offset:1024
	ds_read_b128 v[192:195], v167 offset:2048
	ds_read_b128 v[196:199], v167 offset:3072
	ds_read_b128 v[200:203], v167 offset:4096
	ds_read_b128 v[204:207], v167 offset:5120
	ds_read_b128 v[208:211], v167 offset:6144
	ds_read_b128 v[214:217], v167 offset:7168
	global_load_lds_dwordx4 v140, s[24:25]
	s_add_i32 m0, s52, 0xe000
	s_nop 0
	global_load_lds_dwordx4 v142, s[24:25]
	s_waitcnt vmcnt(8)
	s_waitcnt lgkmcnt(0)
	s_barrier
	s_setprio 1
	s_waitcnt lgkmcnt(0)
	v_mfma_f32_16x16x32_bf16 v[124:127], v[148:151], v[184:187], v[124:127]
	v_mfma_f32_16x16x32_bf16 v[120:123], v[156:159], v[184:187], v[120:123]
	v_mfma_f32_16x16x32_bf16 v[108:111], v[148:151], v[192:195], v[108:111]
	v_mfma_f32_16x16x32_bf16 v[104:107], v[156:159], v[192:195], v[104:107]
	v_mfma_f32_16x16x32_bf16 v[92:95], v[148:151], v[200:203], v[92:95]
	v_mfma_f32_16x16x32_bf16 v[88:91], v[156:159], v[200:203], v[88:91]
	v_mfma_f32_16x16x32_bf16 v[76:79], v[148:151], v[208:211], v[76:79]
	v_mfma_f32_16x16x32_bf16 v[72:75], v[156:159], v[208:211], v[72:75]
	v_mfma_f32_16x16x32_bf16 v[124:127], v[152:155], v[188:191], v[124:127]
	v_mfma_f32_16x16x32_bf16 v[120:123], v[160:163], v[188:191], v[120:123]
	v_mfma_f32_16x16x32_bf16 v[108:111], v[152:155], v[196:199], v[108:111]
	v_mfma_f32_16x16x32_bf16 v[104:107], v[160:163], v[196:199], v[104:107]
	v_mfma_f32_16x16x32_bf16 v[92:95], v[152:155], v[204:207], v[92:95]
	v_mfma_f32_16x16x32_bf16 v[88:91], v[160:163], v[204:207], v[88:91]
	v_mfma_f32_16x16x32_bf16 v[76:79], v[152:155], v[214:217], v[76:79]
	v_mfma_f32_16x16x32_bf16 v[72:75], v[160:163], v[214:217], v[72:75]
	s_setprio 0
	s_setprio 1
	v_mfma_f32_16x16x32_bf16 v[116:119], v[168:171], v[184:187], v[116:119]
	v_mfma_f32_16x16x32_bf16 v[112:115], v[176:179], v[184:187], v[112:115]
	v_mfma_f32_16x16x32_bf16 v[100:103], v[168:171], v[192:195], v[100:103]
	v_mfma_f32_16x16x32_bf16 v[96:99], v[176:179], v[192:195], v[96:99]
	v_mfma_f32_16x16x32_bf16 v[84:87], v[168:171], v[200:203], v[84:87]
	v_mfma_f32_16x16x32_bf16 v[80:83], v[176:179], v[200:203], v[80:83]
	v_mfma_f32_16x16x32_bf16 v[68:71], v[168:171], v[208:211], v[68:71]
	v_mfma_f32_16x16x32_bf16 v[64:67], v[176:179], v[208:211], v[64:67]
	v_mfma_f32_16x16x32_bf16 v[116:119], v[172:175], v[188:191], v[116:119]
	v_mfma_f32_16x16x32_bf16 v[112:115], v[180:183], v[188:191], v[112:115]
	v_mfma_f32_16x16x32_bf16 v[100:103], v[172:175], v[196:199], v[100:103]
	v_mfma_f32_16x16x32_bf16 v[96:99], v[180:183], v[196:199], v[96:99]
	v_mfma_f32_16x16x32_bf16 v[84:87], v[172:175], v[204:207], v[84:87]
	v_mfma_f32_16x16x32_bf16 v[80:83], v[180:183], v[204:207], v[80:83]
	v_mfma_f32_16x16x32_bf16 v[68:71], v[172:175], v[214:217], v[68:71]
	v_mfma_f32_16x16x32_bf16 v[64:67], v[180:183], v[214:217], v[64:67]
	s_setprio 0
	s_barrier
	s_add_i32 s44, s44, s2
	s_mov_b32 m0, s44
	ds_read_b128 v[184:187], v167 offset:16384
	ds_read_b128 v[188:191], v167 offset:17408
	ds_read_b128 v[192:195], v167 offset:18432
	ds_read_b128 v[196:199], v167 offset:19456
	ds_read_b128 v[200:203], v167 offset:20480
	ds_read_b128 v[204:207], v167 offset:21504
	ds_read_b128 v[208:211], v167 offset:22528
	ds_read_b128 v[214:217], v167 offset:23552
	global_load_lds_dwordx4 v132, s[26:27]
	s_add_i32 m0, s44, 0x2000
	s_add_u32 s44, s26, 0x40000
	s_addc_u32 s45, s27, 0
	s_add_i32 s46, s46, s2
	global_load_lds_dwordx4 v128, s[26:27]
	s_mov_b32 m0, s46
	s_nop 0
	global_load_lds_dwordx4 v132, s[44:45]
	s_add_i32 m0, s46, 0x2000
	s_nop 0
	global_load_lds_dwordx4 v128, s[44:45]
	s_mov_b32 m0, s52
	s_nop 0
	global_load_lds_dwordx4 v134, s[36:37]
	s_mov_b32 m0, s53
	s_nop 0
	global_load_lds_dwordx4 v130, s[36:37]
	s_waitcnt vmcnt(8)
	s_waitcnt lgkmcnt(0)
	s_barrier
	s_setprio 1
	s_waitcnt lgkmcnt(0)
	v_mfma_f32_16x16x32_bf16 v[60:63], v[148:151], v[184:187], v[60:63]
	v_mfma_f32_16x16x32_bf16 v[56:59], v[156:159], v[184:187], v[56:59]
	v_mfma_f32_16x16x32_bf16 v[44:47], v[148:151], v[192:195], v[44:47]
	v_mfma_f32_16x16x32_bf16 v[40:43], v[156:159], v[192:195], v[40:43]
	v_mfma_f32_16x16x32_bf16 v[28:31], v[148:151], v[200:203], v[28:31]
	v_mfma_f32_16x16x32_bf16 v[24:27], v[156:159], v[200:203], v[24:27]
	v_mfma_f32_16x16x32_bf16 v[12:15], v[148:151], v[208:211], v[12:15]
	v_mfma_f32_16x16x32_bf16 v[8:11], v[156:159], v[208:211], v[8:11]
	v_mfma_f32_16x16x32_bf16 v[60:63], v[152:155], v[188:191], v[60:63]
	v_mfma_f32_16x16x32_bf16 v[56:59], v[160:163], v[188:191], v[56:59]
	v_mfma_f32_16x16x32_bf16 v[44:47], v[152:155], v[196:199], v[44:47]
	v_mfma_f32_16x16x32_bf16 v[40:43], v[160:163], v[196:199], v[40:43]
	v_mfma_f32_16x16x32_bf16 v[28:31], v[152:155], v[204:207], v[28:31]
	v_mfma_f32_16x16x32_bf16 v[24:27], v[160:163], v[204:207], v[24:27]
	v_mfma_f32_16x16x32_bf16 v[12:15], v[152:155], v[214:217], v[12:15]
	v_mfma_f32_16x16x32_bf16 v[8:11], v[160:163], v[214:217], v[8:11]
	s_setprio 0
	s_setprio 1
	v_mfma_f32_16x16x32_bf16 v[52:55], v[168:171], v[184:187], v[52:55]
	v_mfma_f32_16x16x32_bf16 v[48:51], v[176:179], v[184:187], v[48:51]
	v_mfma_f32_16x16x32_bf16 v[36:39], v[168:171], v[192:195], v[36:39]
	v_mfma_f32_16x16x32_bf16 v[32:35], v[176:179], v[192:195], v[32:35]
	v_mfma_f32_16x16x32_bf16 v[20:23], v[168:171], v[200:203], v[20:23]
	v_mfma_f32_16x16x32_bf16 v[16:19], v[176:179], v[200:203], v[16:19]
	v_mfma_f32_16x16x32_bf16 v[4:7], v[168:171], v[208:211], v[4:7]
	v_mfma_f32_16x16x32_bf16 v[0:3], v[176:179], v[208:211], v[0:3]
	v_mfma_f32_16x16x32_bf16 v[52:55], v[172:175], v[188:191], v[52:55]
	v_mfma_f32_16x16x32_bf16 v[48:51], v[180:183], v[188:191], v[48:51]
	v_mfma_f32_16x16x32_bf16 v[36:39], v[172:175], v[196:199], v[36:39]
	v_mfma_f32_16x16x32_bf16 v[32:35], v[180:183], v[196:199], v[32:35]
	v_mfma_f32_16x16x32_bf16 v[20:23], v[172:175], v[204:207], v[20:23]
	v_mfma_f32_16x16x32_bf16 v[16:19], v[180:183], v[204:207], v[16:19]
	v_mfma_f32_16x16x32_bf16 v[4:7], v[172:175], v[214:217], v[4:7]
	v_mfma_f32_16x16x32_bf16 v[0:3], v[180:183], v[214:217], v[0:3]
	s_setprio 0
	s_barrier
; #define PG8_STAGE(bufoff, gbase, voff) do { _Pragma("unroll") for (int _i = 0; _i < 2; ++_i) \
;         __builtin_amdgcn_global_load_lds((const unsigned*)((const char*)(gbase) + (voff)[_i]), (LAS unsigned*)(lds + (bufoff) + ldsw + _i * 8192), 16, 0, 0); } while (0)
; #define PG8_LDA(dst, b, h) do { _Pragma("unroll") for (int m = 0; m < 4; ++m) _Pragma("unroll") for (int k = 0; k < 2; ++k) dst[m][k] = *(const LAS bf16x8*)(lds + PG8_SA(b, h) + aoff + m * 2048 + k * 1024); } while (0)
; #define PG8_LDB(dst, b, h) do { _Pragma("unroll") for (int n = 0; n < 2; ++n) _Pragma("unroll") for (int k = 0; k < 2; ++k) dst[n][k] = *(const LAS bf16x8*)(lds + PG8_SB(b, h) + boff + n * 2048 + k * 1024); } while (0)
; #define PG8_MMA(ai, bj, At, Bt) do { __builtin_amdgcn_s_setprio(1); _Pragma("unroll") for (int m = 0; m < 4; ++m) _Pragma("unroll") for (int n = 0; n < 2; ++n) _Pragma("unroll") for (int k = 0; k < 2; ++k) \
;         acc[ai][bj][m][n] = __builtin_amdgcn_mfma_f32_16x16x32_bf16(Bt[n][k], At[m][k], acc[ai][bj][m][n], 0, 0, 0); __builtin_amdgcn_s_setprio(0); } while (0)
; #define PG8_WAIT_V(n) asm volatile("s_waitcnt vmcnt(" #n ")" ::: "memory")
; #define PG8_WAIT_L(n) asm volatile("s_waitcnt lgkmcnt(" #n ")" ::: "memory")
; #define PG8_BAR __builtin_amdgcn_s_barrier()
; #define PG8_SCHED __builtin_amdgcn_sched_barrier(0)
; template <class Epi, class Sched>
; __device__ __forceinline__ void gemm_phase(LAS unsigned char* lds, const Gemm g, const Sched& S, const Epi& E) {
;     ...
;             PG8_LDB(B0, 1, 0); PG8_LDB(B1, 1, 1); PG8_SCHED; PG8_LDA(At, 1, 0); PG8_STAGE(PG8_SA(0, 1), a2 + hstepA, voffA);
;             PG8_WAIT_V(8); PG8_WAIT_L(0); PG8_BAR; PG8_MMA(0, 0, At, B0); PG8_MMA(0, 1, At, B1); PG8_BAR; PG8_SCHED;
;             PG8_LDA(At, 1, 1); PG8_STAGE(PG8_SB(1, 0), b3, voffB); PG8_STAGE(PG8_SB(1, 1), b3 + hstepB, voffB); PG8_STAGE(PG8_SA(1, 0), a3, voffA);
;             PG8_WAIT_V(8); PG8_WAIT_L(0); PG8_BAR; PG8_MMA(1, 0, At, B0); PG8_MMA(1, 1, At, B1); PG8_BAR; PG8_SCHED;
;         }
	s_add_i32 s44, 0, 0x18000
	v_add_u32_e32 v145, s44, v165
	s_add_i32 s45, 0, 0x1c000
	ds_read_b128 v[148:151], v145
	ds_read_b128 v[152:155], v145 offset:1024
	ds_read_b128 v[156:159], v145 offset:2048
	ds_read_b128 v[160:163], v145 offset:3072
	v_add_u32_e32 v145, s45, v165
	ds_read_b128 v[168:171], v145
	ds_read_b128 v[172:175], v145 offset:1024
	ds_read_b128 v[176:179], v145 offset:2048
	ds_read_b128 v[180:183], v145 offset:3072
	s_add_u32 s36, s36, 0x40000
	s_addc_u32 s37, s37, 0
	s_mov_b32 m0, s54
	ds_read_b128 v[184:187], v167 offset:32768
	ds_read_b128 v[188:191], v167 offset:33792
	ds_read_b128 v[192:195], v167 offset:34816
	ds_read_b128 v[196:199], v167 offset:35840
	ds_read_b128 v[200:203], v167 offset:36864
	ds_read_b128 v[204:207], v167 offset:37888
	ds_read_b128 v[208:211], v167 offset:38912
	ds_read_b128 v[214:217], v167 offset:39936
	global_load_lds_dwordx4 v134, s[36:37]
	s_mov_b32 m0, s55
	s_nop 0
	global_load_lds_dwordx4 v130, s[36:37]
	s_waitcnt vmcnt(8)
	s_waitcnt lgkmcnt(0)
	s_barrier
	s_setprio 1
	s_waitcnt lgkmcnt(0)
	v_mfma_f32_16x16x32_bf16 v[124:127], v[148:151], v[184:187], v[124:127]
	v_mfma_f32_16x16x32_bf16 v[120:123], v[156:159], v[184:187], v[120:123]
	v_mfma_f32_16x16x32_bf16 v[108:111], v[148:151], v[192:195], v[108:111]
	v_mfma_f32_16x16x32_bf16 v[104:107], v[156:159], v[192:195], v[104:107]
	v_mfma_f32_16x16x32_bf16 v[92:95], v[148:151], v[200:203], v[92:95]
	v_mfma_f32_16x16x32_bf16 v[88:91], v[156:159], v[200:203], v[88:91]
	v_mfma_f32_16x16x32_bf16 v[76:79], v[148:151], v[208:211], v[76:79]
	v_mfma_f32_16x16x32_bf16 v[72:75], v[156:159], v[208:211], v[72:75]
	v_mfma_f32_16x16x32_bf16 v[124:127], v[152:155], v[188:191], v[124:127]
	v_mfma_f32_16x16x32_bf16 v[120:123], v[160:163], v[188:191], v[120:123]
	v_mfma_f32_16x16x32_bf16 v[108:111], v[152:155], v[196:199], v[108:111]
	v_mfma_f32_16x16x32_bf16 v[104:107], v[160:163], v[196:199], v[104:107]
	v_mfma_f32_16x16x32_bf16 v[92:95], v[152:155], v[204:207], v[92:95]
	v_mfma_f32_16x16x32_bf16 v[88:91], v[160:163], v[204:207], v[88:91]
	v_mfma_f32_16x16x32_bf16 v[76:79], v[152:155], v[214:217], v[76:79]
	v_mfma_f32_16x16x32_bf16 v[72:75], v[160:163], v[214:217], v[72:75]
	s_setprio 0
	s_setprio 1
	v_mfma_f32_16x16x32_bf16 v[116:119], v[168:171], v[184:187], v[116:119]
	v_mfma_f32_16x16x32_bf16 v[112:115], v[176:179], v[184:187], v[112:115]
	v_mfma_f32_16x16x32_bf16 v[100:103], v[168:171], v[192:195], v[100:103]
	v_mfma_f32_16x16x32_bf16 v[96:99], v[176:179], v[192:195], v[96:99]
	v_mfma_f32_16x16x32_bf16 v[84:87], v[168:171], v[200:203], v[84:87]
	v_mfma_f32_16x16x32_bf16 v[80:83], v[176:179], v[200:203], v[80:83]
	v_mfma_f32_16x16x32_bf16 v[68:71], v[168:171], v[208:211], v[68:71]
	v_mfma_f32_16x16x32_bf16 v[64:67], v[176:179], v[208:211], v[64:67]
	v_mfma_f32_16x16x32_bf16 v[116:119], v[172:175], v[188:191], v[116:119]
	v_mfma_f32_16x16x32_bf16 v[112:115], v[180:183], v[188:191], v[112:115]
	v_mfma_f32_16x16x32_bf16 v[100:103], v[172:175], v[196:199], v[100:103]
	v_mfma_f32_16x16x32_bf16 v[96:99], v[180:183], v[196:199], v[96:99]
	v_mfma_f32_16x16x32_bf16 v[84:87], v[172:175], v[204:207], v[84:87]
	v_mfma_f32_16x16x32_bf16 v[80:83], v[180:183], v[204:207], v[80:83]
	v_mfma_f32_16x16x32_bf16 v[68:71], v[172:175], v[214:217], v[68:71]
	v_mfma_f32_16x16x32_bf16 v[64:67], v[180:183], v[214:217], v[64:67]
	s_setprio 0
	s_barrier
	s_add_u32 s98, s36, 0xfffc0080
	s_addc_u32 s99, s37, -1
	s_add_u32 s62, s26, 0x80
	s_addc_u32 s63, s27, 0
	s_add_i32 s36, s44, s2
	s_mov_b32 m0, s36
	ds_read_b128 v[184:187], v167 offset:49152
	ds_read_b128 v[188:191], v167 offset:50176
	ds_read_b128 v[192:195], v167 offset:51200
	ds_read_b128 v[196:199], v167 offset:52224
	ds_read_b128 v[200:203], v167 offset:53248
	ds_read_b128 v[204:207], v167 offset:54272
	ds_read_b128 v[208:211], v167 offset:55296
	ds_read_b128 v[214:217], v167 offset:56320
	global_load_lds_dwordx4 v132, s[62:63]
	s_add_i32 m0, s36, 0x2000
	s_add_u32 s26, s26, 0x40080
	s_addc_u32 s27, s27, 0
	s_add_i32 s36, s45, s2
	global_load_lds_dwordx4 v128, s[62:63]
	s_mov_b32 m0, s36
	s_nop 0
	global_load_lds_dwordx4 v132, s[26:27]
	s_add_i32 m0, s36, 0x2000
	s_nop 0
	global_load_lds_dwordx4 v128, s[26:27]
	s_mov_b32 m0, s56
	s_nop 0
	global_load_lds_dwordx4 v134, s[98:99]
	s_mov_b32 m0, s57
	s_nop 0
	global_load_lds_dwordx4 v130, s[98:99]
	s_waitcnt vmcnt(8)
	s_waitcnt lgkmcnt(0)
	s_barrier
	s_setprio 1
	s_waitcnt lgkmcnt(0)
	v_mfma_f32_16x16x32_bf16 v[60:63], v[148:151], v[184:187], v[60:63]
	v_mfma_f32_16x16x32_bf16 v[56:59], v[156:159], v[184:187], v[56:59]
	v_mfma_f32_16x16x32_bf16 v[44:47], v[148:151], v[192:195], v[44:47]
	v_mfma_f32_16x16x32_bf16 v[40:43], v[156:159], v[192:195], v[40:43]
	v_mfma_f32_16x16x32_bf16 v[28:31], v[148:151], v[200:203], v[28:31]
	v_mfma_f32_16x16x32_bf16 v[24:27], v[156:159], v[200:203], v[24:27]
	v_mfma_f32_16x16x32_bf16 v[12:15], v[148:151], v[208:211], v[12:15]
	v_mfma_f32_16x16x32_bf16 v[8:11], v[156:159], v[208:211], v[8:11]
	v_mfma_f32_16x16x32_bf16 v[60:63], v[152:155], v[188:191], v[60:63]
	v_mfma_f32_16x16x32_bf16 v[56:59], v[160:163], v[188:191], v[56:59]
	v_mfma_f32_16x16x32_bf16 v[44:47], v[152:155], v[196:199], v[44:47]
	v_mfma_f32_16x16x32_bf16 v[40:43], v[160:163], v[196:199], v[40:43]
	v_mfma_f32_16x16x32_bf16 v[28:31], v[152:155], v[204:207], v[28:31]
	v_mfma_f32_16x16x32_bf16 v[24:27], v[160:163], v[204:207], v[24:27]
	v_mfma_f32_16x16x32_bf16 v[12:15], v[152:155], v[214:217], v[12:15]
	v_mfma_f32_16x16x32_bf16 v[8:11], v[160:163], v[214:217], v[8:11]
	s_setprio 0
	s_setprio 1
	v_mfma_f32_16x16x32_bf16 v[52:55], v[168:171], v[184:187], v[52:55]
	v_mfma_f32_16x16x32_bf16 v[48:51], v[176:179], v[184:187], v[48:51]
	v_mfma_f32_16x16x32_bf16 v[36:39], v[168:171], v[192:195], v[36:39]
	v_mfma_f32_16x16x32_bf16 v[32:35], v[176:179], v[192:195], v[32:35]
	v_mfma_f32_16x16x32_bf16 v[20:23], v[168:171], v[200:203], v[20:23]
	v_mfma_f32_16x16x32_bf16 v[16:19], v[176:179], v[200:203], v[16:19]
	v_mfma_f32_16x16x32_bf16 v[4:7], v[168:171], v[208:211], v[4:7]
	v_mfma_f32_16x16x32_bf16 v[0:3], v[176:179], v[208:211], v[0:3]
	v_mfma_f32_16x16x32_bf16 v[52:55], v[172:175], v[188:191], v[52:55]
	v_mfma_f32_16x16x32_bf16 v[48:51], v[180:183], v[188:191], v[48:51]
	v_mfma_f32_16x16x32_bf16 v[36:39], v[172:175], v[196:199], v[36:39]
	v_mfma_f32_16x16x32_bf16 v[32:35], v[180:183], v[196:199], v[32:35]
	v_mfma_f32_16x16x32_bf16 v[20:23], v[172:175], v[204:207], v[20:23]
	v_mfma_f32_16x16x32_bf16 v[16:19], v[180:183], v[204:207], v[16:19]
	v_mfma_f32_16x16x32_bf16 v[4:7], v[172:175], v[214:217], v[4:7]
	v_mfma_f32_16x16x32_bf16 v[0:3], v[180:183], v[214:217], v[0:3]
	s_setprio 0
	s_barrier
	s_add_i32 s43, s43, 2
	s_add_u32 s24, s24, 0x100
	s_addc_u32 s25, s25, 0
	s_add_u32 s19, s19, 0x100
	s_addc_u32 s42, s42, 0
	s_cmp_gt_u32 s43, 13
	s_cbranch_scc0 .LBB0_280
	s_and_b64 vcc, exec, s[4:5]
	s_cbranch_vccz .LBB0_283
	s_barrier

; __device__ __forceinline__ unsigned cvt_pk_bf16(float lo, float hi) { unsigned r; asm volatile("v_cvt_pk_bf16_f32 %0, %1, %2" : "=v"(r) : "v"(lo), "v"(hi)); return r; }
;     __device__ __forceinline__ void operator()(f32x4 (&acc)[2][2][4][2], const Unit& u, int wr, int wc, int fr, int fq) const {
;         bf16_t* xb = XR + (size_t)(u.pm * BM + wr * 64) * DM + u.pn * BM;
;         const unsigned lo = (unsigned)(fr * DM + wc * 32 + 8 * fq);
;         u32x4 xv[2][4][2];
; #pragma unroll
;         for (int ai = 0; ai < 2; ++ai)
; #pragma unroll
;             for (int m = 0; m < 4; ++m)
; #pragma unroll
;                 for (int bj = 0; bj < 2; ++bj) xv[ai][m][bj] = *(const u32x4*)(xb + (ai * HALF + m * 16) * DM + bj * HALF + lo);
; #pragma unroll
;         for (int ai = 0; ai < 2; ++ai)
; #pragma unroll
;             for (int m = 0; m < 4; ++m)
; #pragma unroll
;                 for (int bj = 0; bj < 2; ++bj) {
;                     const u32x4 x = xv[ai][m][bj]; const f32x4 v0 = acc[ai][bj][m][0], v1 = acc[ai][bj][m][1];
;                     u32x4 w;
;                     w.x = cvt_pk_bf16(bf_lo(x.x) + v0[0], bf_hi(x.x) + v0[1]); w.y = cvt_pk_bf16(bf_lo(x.y) + v0[2], bf_hi(x.y) + v0[3]);
;                     w.z = cvt_pk_bf16(bf_lo(x.z) + v1[0], bf_hi(x.z) + v1[1]); w.w = cvt_pk_bf16(bf_lo(x.w) + v1[2], bf_hi(x.w) + v1[3]);
;                     *(u32x4*)(xb + (ai * HALF + m * 16) * DM + bj * HALF + lo) = w;
.LBB0_513:
	s_lshl_b32 s14, s48, 8
	s_add_i32 s14, s14, s43
	s_ashr_i32 s15, s14, 31
	s_lshl_b64 s[14:15], s[14:15], 11
	s_add_u32 s17, s34, s14
	s_addc_u32 s19, s35, s15
	s_lshl_b32 s14, s47, 8
	s_ashr_i32 s15, s14, 31
	s_lshl_b64 s[14:15], s[14:15], 1
	s_add_u32 s24, s17, s14
	s_addc_u32 s25, s19, s15
	global_load_dwordx4 v[180:183], v212, s[24:25]
	global_load_dwordx4 v[184:187], v212, s[24:25] offset:256
	v_lshl_add_u64 v[128:129], s[24:25], 0, v[212:213]
	v_add_co_u32_e32 v218, vcc, s11, v128
	s_mov_b32 s14, 0x48000
	s_nop 0
	v_addc_co_u32_e32 v219, vcc, 0, v129, vcc
	global_load_dwordx4 v[188:191], v[218:219], off
	global_load_dwordx4 v[192:195], v[218:219], off offset:256
	v_add_co_u32_e32 v220, vcc, s33, v128
	s_nop 1
	v_addc_co_u32_e32 v221, vcc, 0, v129, vcc
	v_add_co_u32_e32 v176, vcc, s10, v128
	s_nop 1
	v_addc_co_u32_e32 v177, vcc, 0, v129, vcc
	v_add_co_u32_e32 v174, vcc, s69, v128
	s_nop 1
	v_addc_co_u32_e32 v175, vcc, 0, v129, vcc
	v_add_co_u32_e32 v172, vcc, s14, v128
	s_mov_b32 s14, 0x50000
	s_nop 0
	v_addc_co_u32_e32 v173, vcc, 0, v129, vcc
	v_add_co_u32_e32 v170, vcc, s14, v128
	s_mov_b32 s14, 0x58000
	s_nop 0
	v_addc_co_u32_e32 v171, vcc, 0, v129, vcc
	v_add_co_u32_e32 v168, vcc, s14, v128
	s_nop 1
	v_addc_co_u32_e32 v169, vcc, 0, v129, vcc
	global_load_dwordx4 v[196:199], v[220:221], off
	global_load_dwordx4 v[200:203], v[220:221], off offset:256
	global_load_dwordx4 v[204:207], v[176:177], off
	global_load_dwordx4 v[208:211], v[176:177], off offset:256
	global_load_dwordx4 v[214:217], v[174:175], off
	global_load_dwordx4 v[152:155], v[174:175], off offset:256
	global_load_dwordx4 v[148:151], v[172:173], off
	global_load_dwordx4 v[144:147], v[172:173], off offset:256
	global_load_dwordx4 v[140:143], v[170:171], off
	global_load_dwordx4 v[136:139], v[170:171], off offset:256
	global_load_dwordx4 v[132:135], v[168:169], off
	global_load_dwordx4 v[128:131], v[168:169], off offset:256
	s_waitcnt vmcnt(12)
	v_lshlrev_b32_e32 v222, 16, v180
	v_and_b32_e32 v180, 0xffff0000, v180
	v_lshlrev_b32_e32 v226, 16, v184
	v_lshlrev_b32_e32 v223, 16, v181
	v_and_b32_e32 v181, 0xffff0000, v181
	v_lshlrev_b32_e32 v224, 16, v182
	v_and_b32_e32 v182, 0xffff0000, v182
	v_lshlrev_b32_e32 v225, 16, v183
	v_and_b32_e32 v183, 0xffff0000, v183
	v_and_b32_e32 v184, 0xffff0000, v184
	v_lshlrev_b32_e32 v227, 16, v185
	v_and_b32_e32 v185, 0xffff0000, v185
	v_add_f32_e32 v124, v124, v222
	v_add_f32_e32 v125, v125, v180
	v_add_f32_e32 v180, v116, v226
	v_cvt_pk_bf16_f32 v116, v124, v125
	v_lshlrev_b32_e32 v228, 16, v186
	v_and_b32_e32 v186, 0xffff0000, v186
	v_add_f32_e32 v126, v126, v223
	v_add_f32_e32 v127, v127, v181
	v_add_f32_e32 v120, v120, v224
	v_add_f32_e32 v121, v121, v182
	v_add_f32_e32 v122, v122, v225
	v_add_f32_e32 v123, v123, v183
	v_add_f32_e32 v181, v117, v184
	v_add_f32_e32 v182, v118, v227
	v_add_f32_e32 v183, v119, v185
	v_cvt_pk_bf16_f32 v117, v126, v127
	v_cvt_pk_bf16_f32 v118, v120, v121
	v_cvt_pk_bf16_f32 v119, v122, v123
	global_store_dwordx4 v212, v[116:119], s[24:25]
	v_lshlrev_b32_e32 v229, 16, v187
	v_add_f32_e32 v184, v108, v228
	v_and_b32_e32 v116, 0xffff0000, v187
	v_add_f32_e32 v185, v109, v186
	v_cvt_pk_bf16_f32 v108, v180, v181
	v_cvt_pk_bf16_f32 v109, v182, v183
	v_add_f32_e32 v111, v111, v116
	v_add_f32_e32 v186, v110, v229
	v_cvt_pk_bf16_f32 v110, v184, v185
	v_cvt_pk_bf16_f32 v111, v186, v111
	global_store_dwordx4 v212, v[108:111], s[24:25] offset:256
	s_andn2_b64 vcc, exec, s[38:39]
	s_mov_b64 s[14:15], -1
	v_lshlrev_b32_e32 v108, 16, v188
	v_and_b32_e32 v109, 0xffff0000, v188
	v_add_f32_e32 v108, v112, v108
	v_add_f32_e32 v109, v113, v109
	v_cvt_pk_bf16_f32 v108, v108, v109
	v_lshlrev_b32_e32 v109, 16, v189
	v_and_b32_e32 v110, 0xffff0000, v189
	v_add_f32_e32 v109, v114, v109
	v_add_f32_e32 v110, v115, v110
	v_cvt_pk_bf16_f32 v109, v109, v110
	v_lshlrev_b32_e32 v110, 16, v190
	v_add_f32_e32 v104, v104, v110
	v_and_b32_e32 v110, 0xffff0000, v190
	v_add_f32_e32 v105, v105, v110
	v_cvt_pk_bf16_f32 v110, v104, v105
	v_lshlrev_b32_e32 v104, 16, v191
	v_add_f32_e32 v104, v106, v104
	v_and_b32_e32 v105, 0xffff0000, v191
	v_add_f32_e32 v105, v107, v105
	v_cvt_pk_bf16_f32 v111, v104, v105
	v_lshlrev_b32_e32 v104, 16, v192
	v_add_f32_e32 v100, v100, v104
	v_and_b32_e32 v104, 0xffff0000, v192
	v_add_f32_e32 v101, v101, v104
	global_store_dwordx4 v[218:219], v[108:111], off
	v_cvt_pk_bf16_f32 v100, v100, v101
	v_lshlrev_b32_e32 v101, 16, v193
	v_add_f32_e32 v101, v102, v101
	v_and_b32_e32 v102, 0xffff0000, v193
	v_add_f32_e32 v102, v103, v102
	v_cvt_pk_bf16_f32 v101, v101, v102
	v_lshlrev_b32_e32 v102, 16, v194
	v_add_f32_e32 v92, v92, v102
	v_and_b32_e32 v102, 0xffff0000, v194
	v_add_f32_e32 v93, v93, v102
	v_cvt_pk_bf16_f32 v102, v92, v93
	v_lshlrev_b32_e32 v92, 16, v195
	v_and_b32_e32 v93, 0xffff0000, v195
	v_add_f32_e32 v92, v94, v92
	v_add_f32_e32 v93, v95, v93
	v_cvt_pk_bf16_f32 v103, v92, v93
	s_waitcnt vmcnt(14)
	v_lshlrev_b32_e32 v92, 16, v196
	v_and_b32_e32 v93, 0xffff0000, v196
	v_add_f32_e32 v92, v96, v92
	v_add_f32_e32 v93, v97, v93
	global_store_dwordx4 v[218:219], v[100:103], off offset:256
	v_cvt_pk_bf16_f32 v92, v92, v93
	v_lshlrev_b32_e32 v93, 16, v197
	v_and_b32_e32 v94, 0xffff0000, v197
	v_add_f32_e32 v93, v98, v93
	v_add_f32_e32 v94, v99, v94
	v_cvt_pk_bf16_f32 v93, v93, v94
	v_lshlrev_b32_e32 v94, 16, v198
	v_add_f32_e32 v88, v88, v94
	v_and_b32_e32 v94, 0xffff0000, v198
	v_add_f32_e32 v89, v89, v94
	v_cvt_pk_bf16_f32 v94, v88, v89
	v_lshlrev_b32_e32 v88, 16, v199
	v_add_f32_e32 v88, v90, v88
	v_and_b32_e32 v89, 0xffff0000, v199
	v_add_f32_e32 v89, v91, v89
	v_cvt_pk_bf16_f32 v95, v88, v89
	s_waitcnt vmcnt(14)
; __device__ __forceinline__ unsigned cvt_pk_bf16(float lo, float hi) { unsigned r; asm volatile("v_cvt_pk_bf16_f32 %0, %1, %2" : "=v"(r) : "v"(lo), "v"(hi)); return r; }
;     __device__ __forceinline__ void operator()(f32x4 (&acc)[2][2][4][2], const Unit& u, int wr, int wc, int fr, int fq) const {
;     ...
;         for (int ai = 0; ai < 2; ++ai)
; #pragma unroll
;             for (int m = 0; m < 4; ++m)
; #pragma unroll
;                 for (int bj = 0; bj < 2; ++bj) {
;                     const u32x4 x = xv[ai][m][bj]; const f32x4 v0 = acc[ai][bj][m][0], v1 = acc[ai][bj][m][1];
;                     u32x4 w;
;                     w.x = cvt_pk_bf16(bf_lo(x.x) + v0[0], bf_hi(x.x) + v0[1]); w.y = cvt_pk_bf16(bf_lo(x.y) + v0[2], bf_hi(x.y) + v0[3]);
;                     w.z = cvt_pk_bf16(bf_lo(x.z) + v1[0], bf_hi(x.z) + v1[1]); w.w = cvt_pk_bf16(bf_lo(x.w) + v1[2], bf_hi(x.w) + v1[3]);
;                     *(u32x4*)(xb + (ai * HALF + m * 16) * DM + bj * HALF + lo) = w;
	v_lshlrev_b32_e32 v88, 16, v200
	v_add_f32_e32 v84, v84, v88
	v_and_b32_e32 v88, 0xffff0000, v200
	v_add_f32_e32 v85, v85, v88
	global_store_dwordx4 v[220:221], v[92:95], off
	v_cvt_pk_bf16_f32 v84, v84, v85
	v_lshlrev_b32_e32 v85, 16, v201
	v_add_f32_e32 v85, v86, v85
	v_and_b32_e32 v86, 0xffff0000, v201
	v_add_f32_e32 v86, v87, v86
	v_cvt_pk_bf16_f32 v85, v85, v86
	v_lshlrev_b32_e32 v86, 16, v202
	v_add_f32_e32 v76, v76, v86
	v_and_b32_e32 v86, 0xffff0000, v202
	v_add_f32_e32 v77, v77, v86
	v_cvt_pk_bf16_f32 v86, v76, v77
	v_lshlrev_b32_e32 v76, 16, v203
	v_and_b32_e32 v77, 0xffff0000, v203
	v_add_f32_e32 v76, v78, v76
	v_add_f32_e32 v77, v79, v77
	v_cvt_pk_bf16_f32 v87, v76, v77
	s_waitcnt vmcnt(14)
	v_lshlrev_b32_e32 v76, 16, v204
	v_and_b32_e32 v77, 0xffff0000, v204
	v_add_f32_e32 v76, v80, v76
	v_add_f32_e32 v77, v81, v77
	global_store_dwordx4 v[220:221], v[84:87], off offset:256
	v_cvt_pk_bf16_f32 v76, v76, v77
	v_lshlrev_b32_e32 v77, 16, v205
	v_and_b32_e32 v78, 0xffff0000, v205
	v_add_f32_e32 v77, v82, v77
	v_add_f32_e32 v78, v83, v78
	v_cvt_pk_bf16_f32 v77, v77, v78
	v_lshlrev_b32_e32 v78, 16, v206
	v_add_f32_e32 v72, v72, v78
	v_and_b32_e32 v78, 0xffff0000, v206
	v_add_f32_e32 v73, v73, v78
	v_cvt_pk_bf16_f32 v78, v72, v73
	v_lshlrev_b32_e32 v72, 16, v207
	v_add_f32_e32 v72, v74, v72
	v_and_b32_e32 v73, 0xffff0000, v207
	v_add_f32_e32 v73, v75, v73
	v_cvt_pk_bf16_f32 v79, v72, v73
	s_waitcnt vmcnt(14)
	v_lshlrev_b32_e32 v72, 16, v208
	v_add_f32_e32 v68, v68, v72
	v_and_b32_e32 v72, 0xffff0000, v208
	v_add_f32_e32 v69, v69, v72
	global_store_dwordx4 v[176:177], v[76:79], off
	v_cvt_pk_bf16_f32 v68, v68, v69
	v_lshlrev_b32_e32 v69, 16, v209
	v_add_f32_e32 v69, v70, v69
	v_and_b32_e32 v70, 0xffff0000, v209
	v_add_f32_e32 v70, v71, v70
	v_cvt_pk_bf16_f32 v69, v69, v70
	v_lshlrev_b32_e32 v70, 16, v210
	v_add_f32_e32 v64, v64, v70
	v_and_b32_e32 v70, 0xffff0000, v210
	v_add_f32_e32 v65, v65, v70
	v_cvt_pk_bf16_f32 v70, v64, v65
	v_lshlrev_b32_e32 v64, 16, v211
	v_add_f32_e32 v64, v66, v64
	v_and_b32_e32 v65, 0xffff0000, v211
	v_add_f32_e32 v65, v67, v65
	v_cvt_pk_bf16_f32 v71, v64, v65
	s_waitcnt vmcnt(14)
	v_lshlrev_b32_e32 v64, 16, v214
	v_add_f32_e32 v60, v60, v64
	v_and_b32_e32 v64, 0xffff0000, v214
	v_add_f32_e32 v61, v61, v64
	global_store_dwordx4 v[176:177], v[68:71], off offset:256
	v_cvt_pk_bf16_f32 v60, v60, v61
	v_lshlrev_b32_e32 v61, 16, v215
	v_add_f32_e32 v61, v62, v61
	v_and_b32_e32 v62, 0xffff0000, v215
	v_add_f32_e32 v62, v63, v62
	v_cvt_pk_bf16_f32 v61, v61, v62
	v_lshlrev_b32_e32 v62, 16, v216
	v_add_f32_e32 v56, v56, v62
	v_and_b32_e32 v62, 0xffff0000, v216
	v_add_f32_e32 v57, v57, v62
	v_cvt_pk_bf16_f32 v62, v56, v57
	v_lshlrev_b32_e32 v56, 16, v217
	v_add_f32_e32 v56, v58, v56
	v_and_b32_e32 v57, 0xffff0000, v217
	v_add_f32_e32 v57, v59, v57
	v_cvt_pk_bf16_f32 v63, v56, v57
	s_waitcnt vmcnt(14)
	v_lshlrev_b32_e32 v56, 16, v152
	v_add_f32_e32 v52, v52, v56
	v_and_b32_e32 v56, 0xffff0000, v152
	v_add_f32_e32 v53, v53, v56
	global_store_dwordx4 v[174:175], v[60:63], off
	v_cvt_pk_bf16_f32 v52, v52, v53
	v_lshlrev_b32_e32 v53, 16, v153
	v_add_f32_e32 v53, v54, v53
	v_and_b32_e32 v54, 0xffff0000, v153
	v_add_f32_e32 v54, v55, v54
	v_cvt_pk_bf16_f32 v53, v53, v54
	v_lshlrev_b32_e32 v54, 16, v154
	v_add_f32_e32 v44, v44, v54
	v_and_b32_e32 v54, 0xffff0000, v154
	v_add_f32_e32 v45, v45, v54
	v_cvt_pk_bf16_f32 v54, v44, v45
	v_lshlrev_b32_e32 v44, 16, v155
	v_and_b32_e32 v45, 0xffff0000, v155
	v_add_f32_e32 v44, v46, v44
	v_add_f32_e32 v45, v47, v45
	v_cvt_pk_bf16_f32 v55, v44, v45
	s_waitcnt vmcnt(14)
	v_lshlrev_b32_e32 v44, 16, v148
	v_and_b32_e32 v45, 0xffff0000, v148
	v_add_f32_e32 v44, v48, v44
	v_add_f32_e32 v45, v49, v45
	global_store_dwordx4 v[174:175], v[52:55], off offset:256
	v_cvt_pk_bf16_f32 v44, v44, v45
	v_lshlrev_b32_e32 v45, 16, v149
	v_and_b32_e32 v46, 0xffff0000, v149
	v_add_f32_e32 v45, v50, v45
	v_add_f32_e32 v46, v51, v46
	v_cvt_pk_bf16_f32 v45, v45, v46
	v_lshlrev_b32_e32 v46, 16, v150
	v_add_f32_e32 v40, v40, v46
	v_and_b32_e32 v46, 0xffff0000, v150
	v_add_f32_e32 v41, v41, v46
	v_cvt_pk_bf16_f32 v46, v40, v41
	v_lshlrev_b32_e32 v40, 16, v151
	v_add_f32_e32 v40, v42, v40
	v_and_b32_e32 v41, 0xffff0000, v151
	v_add_f32_e32 v41, v43, v41
	v_cvt_pk_bf16_f32 v47, v40, v41
	s_waitcnt vmcnt(14)
; __device__ __forceinline__ unsigned cvt_pk_bf16(float lo, float hi) { unsigned r; asm volatile("v_cvt_pk_bf16_f32 %0, %1, %2" : "=v"(r) : "v"(lo), "v"(hi)); return r; }
; #define PG8_BAR __builtin_amdgcn_s_barrier()
;     __device__ __forceinline__ void operator()(f32x4 (&acc)[2][2][4][2], const Unit& u, int wr, int wc, int fr, int fq) const {
;     ...
;         for (int ai = 0; ai < 2; ++ai)
; #pragma unroll
;             for (int m = 0; m < 4; ++m)
; #pragma unroll
;                 for (int bj = 0; bj < 2; ++bj) {
;                     const u32x4 x = xv[ai][m][bj]; const f32x4 v0 = acc[ai][bj][m][0], v1 = acc[ai][bj][m][1];
;                     u32x4 w;
;                     w.x = cvt_pk_bf16(bf_lo(x.x) + v0[0], bf_hi(x.x) + v0[1]); w.y = cvt_pk_bf16(bf_lo(x.y) + v0[2], bf_hi(x.y) + v0[3]);
;                     w.z = cvt_pk_bf16(bf_lo(x.z) + v1[0], bf_hi(x.z) + v1[1]); w.w = cvt_pk_bf16(bf_lo(x.w) + v1[2], bf_hi(x.w) + v1[3]);
;                     *(u32x4*)(xb + (ai * HALF + m * 16) * DM + bj * HALF + lo) = w;
; template <class Epi, class Sched>
; __device__ __forceinline__ void gemm_phase(LAS unsigned char* lds, const Gemm g, const Sched& S, const Epi& E) {
;     ...
;         if (!has_next) break;
;         if (!(Epi::CHAIN && nxt.b != 0)) {
; #pragma unroll
;         for (int a = 0; a < 2; ++a)
; #pragma unroll
;             for (int b = 0; b < 2; ++b)
; #pragma unroll
;                 for (int m = 0; m < 4; ++m)
; #pragma unroll
;                     for (int n = 0; n < 2; ++n) acc[a][b][m][n] = (f32x4){0.f, 0.f, 0.f, 0.f};
;         }
;         cur = nxt; cA = nA; cB = nB; ++ui;
;         if (wr == 1) PG8_BAR;
	v_lshlrev_b32_e32 v40, 16, v144
	v_add_f32_e32 v36, v36, v40
	v_and_b32_e32 v40, 0xffff0000, v144
	v_add_f32_e32 v37, v37, v40
	global_store_dwordx4 v[172:173], v[44:47], off
	v_cvt_pk_bf16_f32 v36, v36, v37
	v_lshlrev_b32_e32 v37, 16, v145
	v_add_f32_e32 v37, v38, v37
	v_and_b32_e32 v38, 0xffff0000, v145
	v_add_f32_e32 v38, v39, v38
	v_cvt_pk_bf16_f32 v37, v37, v38
	v_lshlrev_b32_e32 v38, 16, v146
	v_add_f32_e32 v28, v28, v38
	v_and_b32_e32 v38, 0xffff0000, v146
	v_add_f32_e32 v29, v29, v38
	v_cvt_pk_bf16_f32 v38, v28, v29
	v_lshlrev_b32_e32 v28, 16, v147
	v_and_b32_e32 v29, 0xffff0000, v147
	v_add_f32_e32 v28, v30, v28
	v_add_f32_e32 v29, v31, v29
	v_cvt_pk_bf16_f32 v39, v28, v29
	s_waitcnt vmcnt(14)
	v_lshlrev_b32_e32 v28, 16, v140
	v_and_b32_e32 v29, 0xffff0000, v140
	v_add_f32_e32 v28, v32, v28
	v_add_f32_e32 v29, v33, v29
	global_store_dwordx4 v[172:173], v[36:39], off offset:256
	v_cvt_pk_bf16_f32 v28, v28, v29
	v_lshlrev_b32_e32 v29, 16, v141
	v_and_b32_e32 v30, 0xffff0000, v141
	v_add_f32_e32 v29, v34, v29
	v_add_f32_e32 v30, v35, v30
	v_cvt_pk_bf16_f32 v29, v29, v30
	v_lshlrev_b32_e32 v30, 16, v142
	v_add_f32_e32 v24, v24, v30
	v_and_b32_e32 v30, 0xffff0000, v142
	v_add_f32_e32 v25, v25, v30
	v_cvt_pk_bf16_f32 v30, v24, v25
	v_lshlrev_b32_e32 v24, 16, v143
	v_add_f32_e32 v24, v26, v24
	v_and_b32_e32 v25, 0xffff0000, v143
	v_add_f32_e32 v25, v27, v25
	v_cvt_pk_bf16_f32 v31, v24, v25
	s_waitcnt vmcnt(14)
	v_lshlrev_b32_e32 v24, 16, v136
	v_add_f32_e32 v20, v20, v24
	v_and_b32_e32 v24, 0xffff0000, v136
	v_add_f32_e32 v21, v21, v24
	global_store_dwordx4 v[170:171], v[28:31], off
	v_cvt_pk_bf16_f32 v20, v20, v21
	v_lshlrev_b32_e32 v21, 16, v137
	v_add_f32_e32 v21, v22, v21
	v_and_b32_e32 v22, 0xffff0000, v137
	v_add_f32_e32 v22, v23, v22
	v_cvt_pk_bf16_f32 v21, v21, v22
	v_lshlrev_b32_e32 v22, 16, v138
	v_add_f32_e32 v12, v12, v22
	v_and_b32_e32 v22, 0xffff0000, v138
	v_add_f32_e32 v13, v13, v22
	v_cvt_pk_bf16_f32 v22, v12, v13
	v_lshlrev_b32_e32 v12, 16, v139
	v_and_b32_e32 v13, 0xffff0000, v139
	v_add_f32_e32 v12, v14, v12
	v_add_f32_e32 v13, v15, v13
	v_cvt_pk_bf16_f32 v23, v12, v13
	s_waitcnt vmcnt(14)
	v_lshlrev_b32_e32 v12, 16, v132
	v_and_b32_e32 v13, 0xffff0000, v132
	v_add_f32_e32 v12, v16, v12
	v_add_f32_e32 v13, v17, v13
	global_store_dwordx4 v[170:171], v[20:23], off offset:256
	v_cvt_pk_bf16_f32 v12, v12, v13
	v_lshlrev_b32_e32 v13, 16, v133
	v_and_b32_e32 v14, 0xffff0000, v133
	v_add_f32_e32 v13, v18, v13
	v_add_f32_e32 v14, v19, v14
	v_cvt_pk_bf16_f32 v13, v13, v14
	v_lshlrev_b32_e32 v14, 16, v134
	v_add_f32_e32 v8, v8, v14
	v_and_b32_e32 v14, 0xffff0000, v134
	v_add_f32_e32 v9, v9, v14
	v_cvt_pk_bf16_f32 v14, v8, v9
	v_lshlrev_b32_e32 v8, 16, v135
	v_add_f32_e32 v8, v10, v8
	v_and_b32_e32 v9, 0xffff0000, v135
	v_add_f32_e32 v9, v11, v9
	v_cvt_pk_bf16_f32 v15, v8, v9
	s_waitcnt vmcnt(14)
	v_lshlrev_b32_e32 v8, 16, v128
	v_add_f32_e32 v4, v4, v8
	v_and_b32_e32 v8, 0xffff0000, v128
	v_add_f32_e32 v5, v5, v8
	global_store_dwordx4 v[168:169], v[12:15], off
	v_cvt_pk_bf16_f32 v4, v4, v5
	v_lshlrev_b32_e32 v5, 16, v129
	v_add_f32_e32 v5, v6, v5
	v_and_b32_e32 v6, 0xffff0000, v129
	v_add_f32_e32 v6, v7, v6
	v_cvt_pk_bf16_f32 v5, v5, v6
	v_lshlrev_b32_e32 v6, 16, v130
	v_add_f32_e32 v0, v0, v6
	v_and_b32_e32 v6, 0xffff0000, v130
	v_add_f32_e32 v1, v1, v6
	v_cvt_pk_bf16_f32 v6, v0, v1
	v_lshlrev_b32_e32 v0, 16, v131
	v_and_b32_e32 v1, 0xffff0000, v131
	v_add_f32_e32 v0, v2, v0
	v_add_f32_e32 v1, v3, v1
	v_cvt_pk_bf16_f32 v7, v0, v1
	global_store_dwordx4 v[168:169], v[4:7], off offset:256
	s_cbranch_vccnz .LBB0_502
	s_andn2_b64 vcc, exec, s[0:1]
	s_cbranch_vccnz .LBB0_501
	s_barrier
	s_branch .LBB0_501
